# v16 plus grid-barrier spin polls with s_sleep 1 instead of s_sleep 3
# speedup vs baseline: 1.0030x; 1.0011x over previous
; __device__ __forceinline__ unsigned xb_ld(unsigned* p)              { return __hip_atomic_load(p, __ATOMIC_RELAXED, __HIP_MEMORY_SCOPE_AGENT); }
; __device__ __forceinline__ unsigned xb_add(unsigned* p, unsigned v) { return __hip_atomic_fetch_add(p, v, __ATOMIC_RELAXED, __HIP_MEMORY_SCOPE_AGENT); }
; #define XB_SPIN(cond, bar) do { unsigned _sp = 0; while (cond) { __builtin_amdgcn_s_sleep(3); \
;     if ((++_sp & 255u) == 0u) { if (xb_ld(&(bar)[XB_TMO])) break; if (_sp > XB_SPIN_CAP) { atomicAdd(&(bar)[XB_TMO], 1u); break; } } } } while (0)
; __device__ __forceinline__ void xcd_barrier(const XcdBarrier& b) {
;     ...
;             const unsigned og = xb_add(&bar[XB_TOP], 1u);
;             const unsigned tg = og / nx;
;             if (og + 1u == (tg + 1u) * nx) xb_add(&bar[XB_TOPGEN], 1u);
;             else XB_SPIN(xb_ld(&bar[XB_TOPGEN]) == tg, bar);
;             __builtin_amdgcn_fence(__ATOMIC_ACQUIRE, "agent");
;             xb_add(&bar[XB_XGEN(b.x)], 1u);
;             asm volatile("s_waitcnt vmcnt(0)" ::: "memory");
;         } else {
;             XB_SPIN(xb_ld(&bar[XB_XGEN(b.x)]) == gen, bar);
.LBB0_91:
	s_and_b32 s2, s1, 0xff
	s_mov_b64 s[26:27], -1
	s_cmp_lg_u32 s2, 0
	s_mov_b64 s[30:31], -1
	s_sleep 1
	s_cbranch_scc1 .LBB0_94
	global_load_dword v2, v0, s[6:7] offset:512 sc1
	s_waitcnt vmcnt(0)
	v_cmp_eq_u32_e32 vcc, 0, v2
	s_cbranch_vccnz .LBB0_96
	s_mov_b64 s[30:31], 0
	s_mov_b64 s[28:29], -1

; __device__ __forceinline__ unsigned xb_ld(unsigned* p)              { return __hip_atomic_load(p, __ATOMIC_RELAXED, __HIP_MEMORY_SCOPE_AGENT); }
; __device__ __forceinline__ unsigned xb_add(unsigned* p, unsigned v) { return __hip_atomic_fetch_add(p, v, __ATOMIC_RELAXED, __HIP_MEMORY_SCOPE_AGENT); }
; #define XB_SPIN(cond, bar) do { unsigned _sp = 0; while (cond) { __builtin_amdgcn_s_sleep(3); \
;     if ((++_sp & 255u) == 0u) { if (xb_ld(&(bar)[XB_TMO])) break; if (_sp > XB_SPIN_CAP) { atomicAdd(&(bar)[XB_TMO], 1u); break; } } } } while (0)
; __device__ __forceinline__ void xcd_barrier(const XcdBarrier& b) {
;     ...
;             const unsigned og = xb_add(&bar[XB_TOP], 1u);
;             const unsigned tg = og / nx;
;             if (og + 1u == (tg + 1u) * nx) xb_add(&bar[XB_TOPGEN], 1u);
;             else XB_SPIN(xb_ld(&bar[XB_TOPGEN]) == tg, bar);
;             __builtin_amdgcn_fence(__ATOMIC_ACQUIRE, "agent");
;             xb_add(&bar[XB_XGEN(b.x)], 1u);
;             asm volatile("s_waitcnt vmcnt(0)" ::: "memory");
;         } else {
;             XB_SPIN(xb_ld(&bar[XB_XGEN(b.x)]) == gen, bar);
.LBB0_108:
	s_and_b32 s2, s1, 0xff
	s_cmp_lg_u32 s2, 0
	s_mov_b64 s[28:29], -1
	s_sleep 1
	s_cbranch_scc1 .LBB0_111
	global_load_dword v1, v0, s[20:21] sc1
	s_waitcnt vmcnt(0)
	v_cmp_eq_u32_e32 vcc, 0, v1
	s_cbranch_vccnz .LBB0_113
	s_mov_b64 s[28:29], 0
	s_mov_b64 s[26:27], -1

; __device__ __forceinline__ unsigned xb_ld(unsigned* p)              { return __hip_atomic_load(p, __ATOMIC_RELAXED, __HIP_MEMORY_SCOPE_AGENT); }
; __device__ __forceinline__ unsigned xb_add(unsigned* p, unsigned v) { return __hip_atomic_fetch_add(p, v, __ATOMIC_RELAXED, __HIP_MEMORY_SCOPE_AGENT); }
; #define XB_SPIN(cond, bar) do { unsigned _sp = 0; while (cond) { __builtin_amdgcn_s_sleep(3); \
;     if ((++_sp & 255u) == 0u) { if (xb_ld(&(bar)[XB_TMO])) break; if (_sp > XB_SPIN_CAP) { atomicAdd(&(bar)[XB_TMO], 1u); break; } } } } while (0)
; __device__ __forceinline__ void xcd_barrier(const XcdBarrier& b) {
;     ...
;             const unsigned og = xb_add(&bar[XB_TOP], 1u);
;             const unsigned tg = og / nx;
;             if (og + 1u == (tg + 1u) * nx) xb_add(&bar[XB_TOPGEN], 1u);
;             else XB_SPIN(xb_ld(&bar[XB_TOPGEN]) == tg, bar);
;             __builtin_amdgcn_fence(__ATOMIC_ACQUIRE, "agent");
;             xb_add(&bar[XB_XGEN(b.x)], 1u);
;             asm volatile("s_waitcnt vmcnt(0)" ::: "memory");
;         } else {
;             XB_SPIN(xb_ld(&bar[XB_XGEN(b.x)]) == gen, bar);
.LBB0_224:
	s_and_b32 s12, s3, 0xff
	s_mov_b64 s[26:27], -1
	s_cmp_lg_u32 s12, 0
	s_mov_b64 s[30:31], -1
	s_sleep 1
	s_cbranch_scc1 .LBB0_227
	global_load_dword v2, v0, s[6:7] offset:512 sc1
	s_waitcnt vmcnt(0)
	v_cmp_eq_u32_e32 vcc, 0, v2
	s_cbranch_vccnz .LBB0_229
	s_mov_b64 s[30:31], 0
	s_mov_b64 s[28:29], -1

; __device__ __forceinline__ unsigned xb_ld(unsigned* p)              { return __hip_atomic_load(p, __ATOMIC_RELAXED, __HIP_MEMORY_SCOPE_AGENT); }
; __device__ __forceinline__ unsigned xb_add(unsigned* p, unsigned v) { return __hip_atomic_fetch_add(p, v, __ATOMIC_RELAXED, __HIP_MEMORY_SCOPE_AGENT); }
; #define XB_SPIN(cond, bar) do { unsigned _sp = 0; while (cond) { __builtin_amdgcn_s_sleep(3); \
;     if ((++_sp & 255u) == 0u) { if (xb_ld(&(bar)[XB_TMO])) break; if (_sp > XB_SPIN_CAP) { atomicAdd(&(bar)[XB_TMO], 1u); break; } } } } while (0)
; __device__ __forceinline__ void xcd_barrier(const XcdBarrier& b) {
;     ...
;             const unsigned og = xb_add(&bar[XB_TOP], 1u);
;             const unsigned tg = og / nx;
;             if (og + 1u == (tg + 1u) * nx) xb_add(&bar[XB_TOPGEN], 1u);
;             else XB_SPIN(xb_ld(&bar[XB_TOPGEN]) == tg, bar);
;             __builtin_amdgcn_fence(__ATOMIC_ACQUIRE, "agent");
;             xb_add(&bar[XB_XGEN(b.x)], 1u);
;             asm volatile("s_waitcnt vmcnt(0)" ::: "memory");
;         } else {
;             XB_SPIN(xb_ld(&bar[XB_XGEN(b.x)]) == gen, bar);
.LBB0_241:
	s_and_b32 s12, s3, 0xff
	s_cmp_lg_u32 s12, 0
	s_mov_b64 s[28:29], -1
	s_sleep 1
	s_cbranch_scc1 .LBB0_244
	global_load_dword v1, v0, s[20:21] sc1
	s_waitcnt vmcnt(0)
	v_cmp_eq_u32_e32 vcc, 0, v1
	s_cbranch_vccnz .LBB0_246
	s_mov_b64 s[28:29], 0
	s_mov_b64 s[26:27], -1

; __device__ __forceinline__ unsigned xb_ld(unsigned* p)              { return __hip_atomic_load(p, __ATOMIC_RELAXED, __HIP_MEMORY_SCOPE_AGENT); }
; __device__ __forceinline__ unsigned xb_add(unsigned* p, unsigned v) { return __hip_atomic_fetch_add(p, v, __ATOMIC_RELAXED, __HIP_MEMORY_SCOPE_AGENT); }
; #define XB_SPIN(cond, bar) do { unsigned _sp = 0; while (cond) { __builtin_amdgcn_s_sleep(3); \
;     if ((++_sp & 255u) == 0u) { if (xb_ld(&(bar)[XB_TMO])) break; if (_sp > XB_SPIN_CAP) { atomicAdd(&(bar)[XB_TMO], 1u); break; } } } } while (0)
; __device__ __forceinline__ void xcd_barrier(const XcdBarrier& b) {
;     ...
;             const unsigned og = xb_add(&bar[XB_TOP], 1u);
;             const unsigned tg = og / nx;
;             if (og + 1u == (tg + 1u) * nx) xb_add(&bar[XB_TOPGEN], 1u);
;             else XB_SPIN(xb_ld(&bar[XB_TOPGEN]) == tg, bar);
;             __builtin_amdgcn_fence(__ATOMIC_ACQUIRE, "agent");
;             xb_add(&bar[XB_XGEN(b.x)], 1u);
;             asm volatile("s_waitcnt vmcnt(0)" ::: "memory");
;         } else {
;             XB_SPIN(xb_ld(&bar[XB_XGEN(b.x)]) == gen, bar);
.LBB0_298:
	s_and_b32 s12, s3, 0xff
	s_mov_b64 s[62:63], -1
	s_cmp_lg_u32 s12, 0
	s_mov_b64 s[66:67], -1
	s_sleep 1
	s_cbranch_scc1 .LBB0_301
	global_load_dword v0, v129, s[6:7] offset:512 sc1
	s_waitcnt vmcnt(0)
	v_cmp_eq_u32_e32 vcc, 0, v0
	s_cbranch_vccnz .LBB0_303
	s_mov_b64 s[66:67], 0
	s_mov_b64 s[64:65], -1

; __device__ __forceinline__ unsigned xb_ld(unsigned* p)              { return __hip_atomic_load(p, __ATOMIC_RELAXED, __HIP_MEMORY_SCOPE_AGENT); }
; __device__ __forceinline__ unsigned xb_add(unsigned* p, unsigned v) { return __hip_atomic_fetch_add(p, v, __ATOMIC_RELAXED, __HIP_MEMORY_SCOPE_AGENT); }
; #define XB_SPIN(cond, bar) do { unsigned _sp = 0; while (cond) { __builtin_amdgcn_s_sleep(3); \
;     if ((++_sp & 255u) == 0u) { if (xb_ld(&(bar)[XB_TMO])) break; if (_sp > XB_SPIN_CAP) { atomicAdd(&(bar)[XB_TMO], 1u); break; } } } } while (0)
; __device__ __forceinline__ void xcd_barrier(const XcdBarrier& b) {
;     ...
;             const unsigned og = xb_add(&bar[XB_TOP], 1u);
;             const unsigned tg = og / nx;
;             if (og + 1u == (tg + 1u) * nx) xb_add(&bar[XB_TOPGEN], 1u);
;             else XB_SPIN(xb_ld(&bar[XB_TOPGEN]) == tg, bar);
;             __builtin_amdgcn_fence(__ATOMIC_ACQUIRE, "agent");
;             xb_add(&bar[XB_XGEN(b.x)], 1u);
;             asm volatile("s_waitcnt vmcnt(0)" ::: "memory");
;         } else {
;             XB_SPIN(xb_ld(&bar[XB_XGEN(b.x)]) == gen, bar);
.LBB0_315:
	s_and_b32 s12, s3, 0xff
	s_mov_b64 s[62:63], -1
	s_cmp_lg_u32 s12, 0
	s_mov_b64 s[66:67], -1
	s_sleep 1
	s_cbranch_scc1 .LBB0_318
	global_load_dword v0, v129, s[52:53] sc1
	s_waitcnt vmcnt(0)
	v_cmp_eq_u32_e32 vcc, 0, v0
	s_cbranch_vccnz .LBB0_320
	s_mov_b64 s[66:67], 0
	s_mov_b64 s[64:65], -1

; __device__ __forceinline__ unsigned xb_ld(unsigned* p)              { return __hip_atomic_load(p, __ATOMIC_RELAXED, __HIP_MEMORY_SCOPE_AGENT); }
; __device__ __forceinline__ unsigned xb_add(unsigned* p, unsigned v) { return __hip_atomic_fetch_add(p, v, __ATOMIC_RELAXED, __HIP_MEMORY_SCOPE_AGENT); }
; #define XB_SPIN(cond, bar) do { unsigned _sp = 0; while (cond) { __builtin_amdgcn_s_sleep(3); \
;     if ((++_sp & 255u) == 0u) { if (xb_ld(&(bar)[XB_TMO])) break; if (_sp > XB_SPIN_CAP) { atomicAdd(&(bar)[XB_TMO], 1u); break; } } } } while (0)
; __device__ __forceinline__ void xcd_barrier(const XcdBarrier& b) {
;     ...
;             const unsigned og = xb_add(&bar[XB_TOP], 1u);
;             const unsigned tg = og / nx;
;             if (og + 1u == (tg + 1u) * nx) xb_add(&bar[XB_TOPGEN], 1u);
;             else XB_SPIN(xb_ld(&bar[XB_TOPGEN]) == tg, bar);
;             __builtin_amdgcn_fence(__ATOMIC_ACQUIRE, "agent");
;             xb_add(&bar[XB_XGEN(b.x)], 1u);
;             asm volatile("s_waitcnt vmcnt(0)" ::: "memory");
;         } else {
;             XB_SPIN(xb_ld(&bar[XB_XGEN(b.x)]) == gen, bar);
.LBB0_499:
	s_and_b32 s1, s0, 0xff
	s_mov_b64 s[62:63], -1
	s_cmp_lg_u32 s1, 0
	s_mov_b64 s[66:67], -1
	s_sleep 1
	s_cbranch_scc1 .LBB0_502
	global_load_dword v0, v129, s[8:9] offset:512 sc1
	s_waitcnt vmcnt(0)
	v_cmp_eq_u32_e32 vcc, 0, v0
	s_cbranch_vccnz .LBB0_504
	s_mov_b64 s[66:67], 0
	s_mov_b64 s[64:65], -1

; __device__ __forceinline__ unsigned xb_ld(unsigned* p)              { return __hip_atomic_load(p, __ATOMIC_RELAXED, __HIP_MEMORY_SCOPE_AGENT); }
; __device__ __forceinline__ unsigned xb_add(unsigned* p, unsigned v) { return __hip_atomic_fetch_add(p, v, __ATOMIC_RELAXED, __HIP_MEMORY_SCOPE_AGENT); }
; #define XB_SPIN(cond, bar) do { unsigned _sp = 0; while (cond) { __builtin_amdgcn_s_sleep(3); \
;     if ((++_sp & 255u) == 0u) { if (xb_ld(&(bar)[XB_TMO])) break; if (_sp > XB_SPIN_CAP) { atomicAdd(&(bar)[XB_TMO], 1u); break; } } } } while (0)
; __device__ __forceinline__ void xcd_barrier(const XcdBarrier& b) {
;     ...
;             const unsigned og = xb_add(&bar[XB_TOP], 1u);
;             const unsigned tg = og / nx;
;             if (og + 1u == (tg + 1u) * nx) xb_add(&bar[XB_TOPGEN], 1u);
;             else XB_SPIN(xb_ld(&bar[XB_TOPGEN]) == tg, bar);
;             __builtin_amdgcn_fence(__ATOMIC_ACQUIRE, "agent");
;             xb_add(&bar[XB_XGEN(b.x)], 1u);
;             asm volatile("s_waitcnt vmcnt(0)" ::: "memory");
;         } else {
;             XB_SPIN(xb_ld(&bar[XB_XGEN(b.x)]) == gen, bar);
.LBB0_516:
	s_and_b32 s1, s0, 0xff
	s_mov_b64 s[62:63], -1
	s_cmp_lg_u32 s1, 0
	s_mov_b64 s[66:67], -1
	s_sleep 1
	s_cbranch_scc1 .LBB0_519
	global_load_dword v0, v129, s[52:53] sc1
	s_waitcnt vmcnt(0)
	v_cmp_eq_u32_e32 vcc, 0, v0
	s_cbranch_vccnz .LBB0_521
	s_mov_b64 s[66:67], 0
	s_mov_b64 s[64:65], -1

; __device__ __forceinline__ unsigned xb_ld(unsigned* p)              { return __hip_atomic_load(p, __ATOMIC_RELAXED, __HIP_MEMORY_SCOPE_AGENT); }
; __device__ __forceinline__ unsigned xb_add(unsigned* p, unsigned v) { return __hip_atomic_fetch_add(p, v, __ATOMIC_RELAXED, __HIP_MEMORY_SCOPE_AGENT); }
; #define XB_SPIN(cond, bar) do { unsigned _sp = 0; while (cond) { __builtin_amdgcn_s_sleep(3); \
;     if ((++_sp & 255u) == 0u) { if (xb_ld(&(bar)[XB_TMO])) break; if (_sp > XB_SPIN_CAP) { atomicAdd(&(bar)[XB_TMO], 1u); break; } } } } while (0)
; __device__ __forceinline__ void xcd_barrier(const XcdBarrier& b) {
;     ...
;             const unsigned og = xb_add(&bar[XB_TOP], 1u);
;             const unsigned tg = og / nx;
;             if (og + 1u == (tg + 1u) * nx) xb_add(&bar[XB_TOPGEN], 1u);
;             else XB_SPIN(xb_ld(&bar[XB_TOPGEN]) == tg, bar);
;             __builtin_amdgcn_fence(__ATOMIC_ACQUIRE, "agent");
;             xb_add(&bar[XB_XGEN(b.x)], 1u);
;             asm volatile("s_waitcnt vmcnt(0)" ::: "memory");
;         } else {
;             XB_SPIN(xb_ld(&bar[XB_XGEN(b.x)]) == gen, bar);
.LBB0_935:
	s_and_b32 s1, s0, 0xff
	s_mov_b64 s[60:61], -1
	s_cmp_lg_u32 s1, 0
	s_mov_b64 s[64:65], -1
	s_sleep 1
	s_cbranch_scc1 .LBB0_938
	global_load_dword v0, v129, s[6:7] offset:512 sc1
	s_waitcnt vmcnt(0)
	v_cmp_eq_u32_e32 vcc, 0, v0
	s_cbranch_vccnz .LBB0_940
	s_mov_b64 s[64:65], 0
	s_mov_b64 s[62:63], -1

; __device__ __forceinline__ unsigned xb_ld(unsigned* p)              { return __hip_atomic_load(p, __ATOMIC_RELAXED, __HIP_MEMORY_SCOPE_AGENT); }
; __device__ __forceinline__ unsigned xb_add(unsigned* p, unsigned v) { return __hip_atomic_fetch_add(p, v, __ATOMIC_RELAXED, __HIP_MEMORY_SCOPE_AGENT); }
; #define XB_SPIN(cond, bar) do { unsigned _sp = 0; while (cond) { __builtin_amdgcn_s_sleep(3); \
;     if ((++_sp & 255u) == 0u) { if (xb_ld(&(bar)[XB_TMO])) break; if (_sp > XB_SPIN_CAP) { atomicAdd(&(bar)[XB_TMO], 1u); break; } } } } while (0)
; __device__ __forceinline__ void xcd_barrier(const XcdBarrier& b) {
;     ...
;             const unsigned og = xb_add(&bar[XB_TOP], 1u);
;             const unsigned tg = og / nx;
;             if (og + 1u == (tg + 1u) * nx) xb_add(&bar[XB_TOPGEN], 1u);
;             else XB_SPIN(xb_ld(&bar[XB_TOPGEN]) == tg, bar);
;             __builtin_amdgcn_fence(__ATOMIC_ACQUIRE, "agent");
;             xb_add(&bar[XB_XGEN(b.x)], 1u);
;             asm volatile("s_waitcnt vmcnt(0)" ::: "memory");
;         } else {
;             XB_SPIN(xb_ld(&bar[XB_XGEN(b.x)]) == gen, bar);
.LBB0_952:
	s_and_b32 s1, s0, 0xff
	s_mov_b64 s[60:61], -1
	s_cmp_lg_u32 s1, 0
	s_mov_b64 s[64:65], -1
	s_sleep 1
	s_cbranch_scc1 .LBB0_955
	global_load_dword v0, v129, s[20:21] sc1
	s_waitcnt vmcnt(0)
	v_cmp_eq_u32_e32 vcc, 0, v0
	s_cbranch_vccnz .LBB0_957
	s_mov_b64 s[64:65], 0
	s_mov_b64 s[62:63], -1
